# retention chunk loop: software L2 prefetch - one dword touch per cache line of the K/Q/V rows needed two chunk steps ahead (incl. next unit), dests are later-overwritten load registers
# baseline (speedup 1.0000x reference)
.LBB0_117:
	s_waitcnt vmcnt(0)
	v_cvt_pk_bf16_f32 v104, v100, v101
	v_cvt_pk_bf16_f32 v105, v102, v103
	s_waitcnt vmcnt(6)
	v_cvt_pk_bf16_f32 v106, v96, v97
	v_cvt_pk_bf16_f32 v107, v98, v99
	ds_write2_b64 v215, v[104:105], v[106:107] offset1:4
	s_waitcnt vmcnt(5)
	v_cvt_pk_bf16_f32 v104, v92, v93
	v_cvt_pk_bf16_f32 v105, v94, v95
	s_waitcnt vmcnt(4)
	v_cvt_pk_bf16_f32 v106, v88, v89
	v_cvt_pk_bf16_f32 v107, v90, v91
	ds_write2_b64 v215, v[104:105], v[106:107] offset0:8 offset1:12
	s_waitcnt vmcnt(3)
	v_cvt_pk_bf16_f32 v104, v84, v85
	v_cvt_pk_bf16_f32 v105, v86, v87
	s_waitcnt vmcnt(2)
	v_cvt_pk_bf16_f32 v106, v80, v81
	v_cvt_pk_bf16_f32 v107, v82, v83
	ds_write2_b64 v216, v[104:105], v[106:107] offset0:160 offset1:164
	s_waitcnt vmcnt(1)
	v_cvt_pk_bf16_f32 v104, v76, v77
	v_cvt_pk_bf16_f32 v105, v78, v79
	s_waitcnt vmcnt(0)
	v_cvt_pk_bf16_f32 v106, v72, v73
	v_cvt_pk_bf16_f32 v107, v74, v75
	ds_write2_b64 v216, v[104:105], v[106:107] offset0:168 offset1:172
	ds_write_b128 v217, v[0:3]
	ds_write_b128 v218, v[4:7]
	ds_write_b128 v219, v[8:11]
	ds_write_b128 v220, v[12:15]
	ds_write_b128 v221, v[28:31]
	ds_write_b128 v222, v[44:47]
	ds_write_b128 v223, v[56:59]
	ds_write_b128 v224, v[60:63]
	ds_write_b128 v225, v[64:67]
	v_lshlrev_b32_e32 v104, 16, v64
	v_and_b32_e32 v105, 0xffff0000, v64
	v_mul_f32_e32 v104, v246, v104
	v_mul_f32_e32 v105, v246, v105
	v_cvt_pk_bf16_f32 v104, v104, v105
	v_lshlrev_b32_e32 v105, 16, v65
	v_and_b32_e32 v106, 0xffff0000, v65
	v_mul_f32_e32 v105, v246, v105
	v_mul_f32_e32 v106, v246, v106
	v_cvt_pk_bf16_f32 v105, v105, v106
	v_lshlrev_b32_e32 v106, 16, v66
	v_and_b32_e32 v107, 0xffff0000, v66
	v_mul_f32_e32 v106, v246, v106
	v_mul_f32_e32 v107, v246, v107
	v_cvt_pk_bf16_f32 v106, v106, v107
	v_lshlrev_b32_e32 v107, 16, v67
	v_mul_f32_e32 v107, v246, v107
	v_and_b32_e32 v108, 0xffff0000, v67
	v_mul_f32_e32 v108, v246, v108
	v_cvt_pk_bf16_f32 v107, v107, v108
	ds_write_b128 v226, v[104:107]
	ds_write_b128 v227, v[68:71]
	v_lshlrev_b32_e32 v104, 16, v68
	v_and_b32_e32 v105, 0xffff0000, v68
	v_mul_f32_e32 v104, v247, v104
	v_mul_f32_e32 v105, v247, v105
	v_cvt_pk_bf16_f32 v104, v104, v105
	v_lshlrev_b32_e32 v105, 16, v69
	v_and_b32_e32 v106, 0xffff0000, v69
	v_mul_f32_e32 v105, v247, v105
	v_mul_f32_e32 v106, v247, v106
	v_cvt_pk_bf16_f32 v105, v105, v106
	v_lshlrev_b32_e32 v106, 16, v70
	v_and_b32_e32 v107, 0xffff0000, v70
	s_add_i32 s51, s52, 1
	v_mul_f32_e32 v106, v247, v106
	v_mul_f32_e32 v107, v247, v107
	s_cmp_ge_u32 s51, s45
	v_cvt_pk_bf16_f32 v106, v106, v107
	v_lshlrev_b32_e32 v107, 16, v71
	s_cselect_b64 s[12:13], -1, 0
	s_cmp_lt_u32 s51, s45
	v_mul_f32_e32 v107, v247, v107
	v_and_b32_e32 v108, 0xffff0000, v71
	s_cselect_b64 s[14:15], -1, 0
	s_and_b64 vcc, exec, s[12:13]
	v_mul_f32_e32 v108, v247, v108
	v_cvt_pk_bf16_f32 v107, v107, v108
	ds_write_b128 v228, v[104:107]
	s_waitcnt lgkmcnt(0)
	s_barrier
	s_add_i32 s34, s52, 2
	s_cmp_lt_u32 s34, s45
	s_cbranch_scc1 .Lrpf_same
	s_add_i32 s35, s40, s96
	s_cmpk_gt_i32 s35, 0x4ff
	s_cbranch_scc1 .Lrpf_done
	s_sub_i32 s34, s34, s45
	s_xor_b32 s35, s34, 1
	s_cmp_lg_u32 s0, 0
	s_cselect_b32 s34, s34, s35
	s_lshl_b32 s34, s34, 7
	s_ashr_i32 s35, s41, 4
	s_lshl_b32 s35, s35, 8
	s_add_i32 vcc_lo, s48, 0x400
	s_cmpk_lt_i32 s40, 0x100
	s_cselect_b32 s35, s35, vcc_lo
	s_add_i32 s34, s34, s35
	s_branch .Lrpf_issue
.Lrpf_same:
	s_sub_i32 s35, s49, s34
	s_cmp_lg_u32 s0, 0
	s_cselect_b32 s34, s34, s35
	s_lshl_b32 s34, s34, 7
	s_add_i32 s34, s34, s48
.Lrpf_issue:
	v_lshrrev_b32_e32 v46, 2, v250
	v_add_u32_e32 v46, s34, v46
	v_mov_b64_e32 v[62:63], s[42:43]
	v_mad_i64_i32 v[62:63], s[34:35], v46, s69, v[62:63]
	v_lshl_add_u64 v[62:63], v[62:63], 0, s[46:47]
	v_and_b32_e32 v46, 3, v250
	v_lshlrev_b32_e32 v46, 7, v46
	v_mov_b32_e32 v47, v145
	v_lshl_add_u64 v[70:71], v[62:63], 0, v[46:47]
	global_load_dword v6, v[70:71], off
	v_add_co_u32_e32 v70, vcc, s68, v70
	s_nop 1
	v_addc_co_u32_e32 v71, vcc, 0, v71, vcc
	global_load_dword v7, v[70:71], off
	v_mov_b32_e32 v46, s10
	v_lshl_add_u64 v[46:47], v[62:63], 0, v[46:47]
	v_add_co_u32_e32 v46, vcc, 0x2000, v46
	s_nop 1
	v_addc_co_u32_e32 v47, vcc, 0, v47, vcc
	global_load_dword v14, v[46:47], off
.Lrpf_done:
	s_and_b64 vcc, exec, s[12:13]
	s_cbranch_vccnz .LBB0_119
	s_sub_i32 s11, s49, s51
	s_and_b64 s[34:35], s[0:1], exec
	s_cselect_b32 s11, s51, s11
	s_lshl_b32 s11, s11, 7
	s_add_i32 s53, s11, s48
	v_add_u32_e32 v0, s53, v236
	v_mov_b64_e32 v[64:65], s[42:43]
	v_mad_i64_i32 v[0:1], s[34:35], v0, s69, v[64:65]
	v_lshl_add_u64 v[0:1], v[0:1], 0, s[46:47]
	v_add_u32_e32 v2, s53, v237
	v_lshl_add_u64 v[0:1], v[0:1], 0, v[144:145]
	v_mad_i64_i32 v[2:3], s[34:35], v2, s69, v[64:65]
	v_add_co_u32_e32 v0, vcc, s68, v0
	v_lshl_add_u64 v[2:3], v[2:3], 0, s[46:47]
	v_add_u32_e32 v8, s53, v238
	v_addc_co_u32_e32 v1, vcc, 0, v1, vcc
	v_lshl_add_u64 v[2:3], v[2:3], 0, v[144:145]
	v_mad_i64_i32 v[8:9], s[34:35], v8, s69, v[64:65]
	v_add_co_u32_e32 v4, vcc, s68, v2
	v_lshl_add_u64 v[8:9], v[8:9], 0, s[46:47]
	v_add_u32_e32 v10, s53, v239
	v_addc_co_u32_e32 v5, vcc, 0, v3, vcc
	v_lshl_add_u64 v[8:9], v[8:9], 0, v[144:145]
	v_mad_i64_i32 v[10:11], s[34:35], v10, s69, v[64:65]
	v_add_co_u32_e32 v8, vcc, s68, v8
	v_lshl_add_u64 v[10:11], v[10:11], 0, s[46:47]
	v_add_u32_e32 v28, s53, v240
	v_addc_co_u32_e32 v9, vcc, 0, v9, vcc
	v_lshl_add_u64 v[10:11], v[10:11], 0, v[144:145]
	v_mad_i64_i32 v[28:29], s[34:35], v28, s69, v[64:65]
	v_add_co_u32_e32 v12, vcc, s68, v10
	v_lshl_add_u64 v[28:29], v[28:29], 0, s[46:47]
	v_add_u32_e32 v30, s53, v241
	v_addc_co_u32_e32 v13, vcc, 0, v11, vcc
	v_lshl_add_u64 v[28:29], v[28:29], 0, v[144:145]
	v_mad_i64_i32 v[30:31], s[34:35], v30, s69, v[64:65]
	v_add_co_u32_e32 v28, vcc, s68, v28
	v_lshl_add_u64 v[30:31], v[30:31], 0, s[46:47]
	v_add_u32_e32 v56, s53, v242
	v_addc_co_u32_e32 v29, vcc, 0, v29, vcc
	v_lshl_add_u64 v[30:31], v[30:31], 0, v[144:145]
	v_mad_i64_i32 v[56:57], s[34:35], v56, s69, v[64:65]
	v_add_co_u32_e32 v44, vcc, s68, v30
	v_lshl_add_u64 v[56:57], v[56:57], 0, s[46:47]
	v_add_u32_e32 v58, s53, v243
	v_addc_co_u32_e32 v45, vcc, 0, v31, vcc
	v_lshl_add_u64 v[56:57], v[56:57], 0, v[144:145]
	v_mad_i64_i32 v[58:59], s[34:35], v58, s69, v[64:65]
	v_add_u32_e32 v66, s53, v244
	v_add_co_u32_e32 v56, vcc, s68, v56
	v_lshl_add_u64 v[58:59], v[58:59], 0, s[46:47]
	v_mad_i64_i32 v[66:67], s[34:35], v66, s69, v[64:65]
	v_addc_co_u32_e32 v57, vcc, 0, v57, vcc
	v_lshl_add_u64 v[58:59], v[58:59], 0, v[144:145]
	v_lshl_add_u64 v[66:67], v[66:67], 0, s[46:47]
	s_mov_b32 s11, s47
	v_add_u32_e32 v68, s53, v245
	v_add_co_u32_e32 v60, vcc, s68, v58
	v_lshl_add_u64 v[66:67], v[66:67], 0, s[10:11]
	v_mov_b32_e32 v157, v145
	v_mad_i64_i32 v[64:65], s[34:35], v68, s69, v[64:65]
	v_addc_co_u32_e32 v61, vcc, 0, v59, vcc
	v_lshl_add_u64 v[66:67], v[66:67], 0, v[156:157]
	v_lshl_add_u64 v[64:65], v[64:65], 0, s[46:47]
	v_add_co_u32_e32 v66, vcc, 0x2000, v66
	v_lshl_add_u64 v[64:65], v[64:65], 0, s[10:11]
	s_nop 0
	v_addc_co_u32_e32 v67, vcc, 0, v67, vcc
	v_lshl_add_u64 v[64:65], v[64:65], 0, v[156:157]
	v_add_co_u32_e32 v68, vcc, 0x2000, v64
	global_load_dwordx4 v[0:3], v[0:1], off
	s_nop 0
	global_load_dwordx4 v[4:7], v[4:5], off
	v_addc_co_u32_e32 v69, vcc, 0, v65, vcc
	global_load_dwordx4 v[8:11], v[8:9], off
	s_nop 0
	global_load_dwordx4 v[12:15], v[12:13], off
	s_nop 0
	global_load_dwordx4 v[28:31], v[28:29], off
	s_nop 0
	global_load_dwordx4 v[44:47], v[44:45], off
	s_nop 0
	global_load_dwordx4 v[56:59], v[56:57], off
	s_nop 0
	global_load_dwordx4 v[60:63], v[60:61], off
	s_nop 0
	global_load_dwordx4 v[64:67], v[66:67], off nt
	s_nop 0
	global_load_dwordx4 v[68:71], v[68:69], off nt
